# sel stream loop: waves 4-7 defer softmax+PV by one barrier interval (stagger); K/V tile prefetch with exact vmcnt and separate address temps
# speedup vs baseline: 1.0060x; 1.0058x over previous
; #define LBAR() do { asm volatile("s_waitcnt lgkmcnt(0)" ::: "memory"); __builtin_amdgcn_s_barrier(); asm volatile("" ::: "memory"); } while (0)
; #define AT_LOAD(s_, k_, v_) do { k_ = *(const u32x4*)(kg + (size_t)(s_) * 4096); v_ = *(const u32x4*)(vg + (s_) * 64); } while (0)
; #define AT_STORE(sb_, k_, v_) do { *(u32x4*)((sb_) + kdst) = k_; *(u32x2*)((sb_) + vdst) = (u32x2){v_.x, v_.y}; *(u32x2*)((sb_) + vdst + 16) = (u32x2){v_.z, v_.w}; } while (0)
; template <int MODE> ...
;     ...
;     float mrun = NEGF, lrun = 0.f;
; #pragma unroll
;     for (int dt = 0; dt < 4; ++dt) o[dt] = (f32x4){0.f, 0.f, 0.f, 0.f};
;     const int crow = tid >> 3, cch = tid & 7;
;     const bf16* kg = K + (size_t)crow * 64 + cch * 8;
;     const bf16* vg = VT + (size_t)crow * 2048 + cch * 8;
;     const int kdst = crow * AKP + cch * 16;
;     const int vdst = 9216 + crow * AKP + ((cch >> 2) * 32 + (cch & 1) * 16 + ((cch & 3) >> 1) * 4) * 2;
;     const int koff = qi * AKP + q4 * 16, voff = 9216 + qi * AKP + q4 * 16;
;     unsigned char* sb0 = lds + AL_KV0; unsigned char* sb1 = sb0 + KV_STAGE;
;     ...
;     u32x4 ka, va, kb = {0u, 0u, 0u, 0u}, vb = {0u, 0u, 0u, 0u};
;     AT_LOAD(st_lo, ka, va);
;     if (st_lo + 1 <= st_hi) AT_LOAD(st_lo + 1, kb, vb);
;     AT_STORE(sb0, ka, va);
;     LBAR();
.LBB0_588:
	v_lshlrev_b32_e32 v45, 5, v60
	v_lshlrev_b32_e32 v46, 2, v60
	v_lshlrev_b32_e32 v116, 3, v44
	s_movk_i32 s0, 0x90
	v_and_b32_e32 v44, 64, v0
	v_and_b32_e32 v45, 32, v45
	v_and_b32_e32 v46, 8, v46
	v_mul_lo_u32 v42, v42, s0
	v_or3_b32 v44, v46, v45, v44
	v_add_u32_e32 v43, v42, v0
	v_add_u32_e32 v42, v42, v44
	v_add_u32_e32 v139, 0x2400, v42
	v_add_u32_e32 v42, 0, v42
	v_add_u32_e32 v141, 0, v43
	v_add_u32_e32 v142, 0xc000, v42
	s_waitcnt vmcnt(1)
	ds_write_b128 v141, v[2:5] offset:40960
	s_waitcnt vmcnt(0)
	ds_write2_b64 v142, v[6:7], v[8:9] offset0:128 offset1:130
	v_lshl_add_u32 v44, v59, 4, v61
	s_and_b32 s0, s38, 1
	s_lshl_b32 s1, s33, 18
	s_waitcnt lgkmcnt(0)
	s_barrier
	v_lshl_add_u64 v[42:43], v[108:109], 0, v[0:1]
	s_lshl_b32 s0, s0, 18
	s_and_b32 s1, s1, 0x380000
	v_add_u32_e32 v143, 0, v44
	v_lshl_add_u64 v[110:111], s[62:63], 0, v[42:43]
	v_lshl_add_u64 v[42:43], v[106:107], 0, v[0:1]
	s_lshl_b32 s12, s69, 17
	v_add_u32_e32 v140, 0x2400, v44
	s_or_b32 s38, s1, s0
	v_add_u32_e32 v144, 0xe800, v143
	v_lshl_add_u64 v[112:113], s[62:63], 0, v[42:43]
	v_sub_u32_e32 v145, v58, v138
	s_add_i32 s13, s80, 0xffffff81
	v_mov_b32_e32 v46, v1
	v_mov_b32_e32 v47, v1
	v_mov_b32_e32 v48, v1
	v_mov_b32_e32 v49, v1
	v_mov_b32_e32 v42, v1
	v_mov_b32_e32 v43, v1
	v_mov_b32_e32 v44, v1
	v_mov_b32_e32 v45, v1
	v_mov_b32_e32 v50, v1
	v_mov_b32_e32 v51, v1
	v_mov_b32_e32 v52, v1
	v_mov_b32_e32 v53, v1
	v_mov_b32_e32 v54, v1
	v_mov_b32_e32 v55, v1
	v_mov_b32_e32 v56, v1
	v_mov_b32_e32 v57, v1
	v_mov_b32_e32 v118, 0xf149f2ca
	v_mov_b32_e32 v117, 0
	s_mov_b32 s14, 3
	s_cmp_lg_u32 s75, 0
	s_cselect_b32 s32, 1, 0
	s_mov_b32 s0, 0
	v_writelane_b32 v255, s0, 60
	v_writelane_b32 v255, s0, 61
	s_branch .LBB0_590

; #define AT_LOAD(s_, k_, v_) do { k_ = *(const u32x4*)(kg + (size_t)(s_) * 4096); v_ = *(const u32x4*)(vg + (s_) * 64); } while (0)
; #define AT_COMPUTE(sb_, s_) do { bool sel_ = true; if (MODE == 0) sel_ = (selm >> (s_)) & 1u; \
;         if ((s_) >= my_lo && (MODE == 1 || __ballot(sel_) != 0ull)) attn_step<MODE>(sb_, s_, qf0, qf1, t, p0, sel_, bias, cfar, o, mrun, lrun, koff, voff, q4); } while (0)
; template <int MODE>
; __device__ __forceinline__ void attn_step(const unsigned char* sb, int st, const bf16x8 qf0, const bf16x8 qf1, int t, int p0, bool sel, const float* bias, float cfar, f32x4 (&o)[4], float& mrun, float& lrun,
;                                           int koff, int voff, int q4) {
;     const int key0 = st * 64;
;     f32x4 s[4];
; #pragma unroll
;     for (int kt = 0; kt < 4; ++kt) {
;         const bf16x8 k0 = *(const bf16x8*)(sb + koff + kt * 16 * AKP), k1 = *(const bf16x8*)(sb + koff + kt * 16 * AKP + 64);
;         s[kt] = (f32x4){0.f, 0.f, 0.f, 0.f};
;         s[kt] = __builtin_amdgcn_mfma_f32_16x16x32_bf16(k0, qf0, s[kt], 0, 0, 0); s[kt] = __builtin_amdgcn_mfma_f32_16x16x32_bf16(k1, qf1, s[kt], 0, 0, 0);
;     }
;     const bool far = (p0 - (key0 + 63) >= BIAS_N - 1) && (MODE == 0 || (p0 + 15 - key0 < 512));
;     bf16x8 vfr[4][2];
; #pragma unroll
;     for (int dt = 0; dt < 4; ++dt) { vfr[dt][0] = *(const bf16x8*)(sb + voff + dt * 16 * AKP); vfr[dt][1] = *(const bf16x8*)(sb + voff + dt * 16 * AKP + 64); }
;     float fsc = 1.f, fc = 0.f;
;     if (far) {
;         fc = (MODE == 0 && !sel) ? MASKV : cfar; fsc = (MODE == 0 && !sel) ? 0.f : SC2;
;     } else {
; #pragma unroll
;         for (int kt = 0; kt < 4; ++kt)
; #pragma unroll
;             for (int j = 0; j < 4; ++j) {
;                 const int dist = t - (key0 + kt * 16 + q4 * 4 + j);
;                 const bool v = (dist >= 0) && (MODE == 0 ? sel : (dist < 512));
;                 const int bi = dist < 0 ? 0 : (dist > BIAS_N - 1 ? BIAS_N - 1 : dist);
;                 const float l = s[kt][j] * SC2 + bias[bi];
;                 s[kt][j] = v ? l : MASKV;
;             }
;     }
; template <int MODE> ...
;     ...
;     for (int st = st_lo; st <= st_hi; st += 2) {
;         if (st + 2 <= st_hi) AT_LOAD(st + 2, ka, va);
;         AT_COMPUTE(sb0, st);
.LBB0_590:
	s_add_i32 s15, s14, -1
	s_cmp_le_u32 s15, s97
	s_cselect_b64 s[6:7], -1, 0
	s_cmp_gt_u32 s15, s97
	s_cbranch_scc1 .LBB0_592
	v_lshl_add_u64 v[248:249], v[112:113], 0, s[38:39]
	v_lshl_add_u64 v[250:251], v[110:111], 0, s[38:39]
	v_add_co_u32_e32 v248, vcc, 0x1a4b8000, v248
	s_nop 1
	v_addc_co_u32_e32 v249, vcc, 0, v249, vcc
	v_add_co_u32_e32 v250, vcc, 0x1a8b4000, v250
	s_nop 1
	v_addc_co_u32_e32 v251, vcc, 0, v251, vcc
	global_load_dwordx4 v[2:5], v[248:249], off offset:2048
	global_load_dwordx4 v[6:9], v[250:251], off offset:2304
.LBB0_592:
	s_cmp_eq_u32 s32, 0
	s_cbranch_scc1 .Lsel_X_go
	v_readlane_b32 s10, v255, 60
	s_nop 3
	s_cmp_eq_u32 s10, 0
	s_cbranch_scc1 .Lsel_X_go
	s_branch .Lsel_BdY
.Lsel_X_go:
	s_add_i32 s16, s14, -3
	s_waitcnt lgkmcnt(2)
	v_lshrrev_b32_e32 v120, s16, v115
	v_and_b32_e32 v58, 1, v120
	v_cmp_eq_u32_e64 s[0:1], 1, v58
	v_bfe_u32 v58, v115, s16, 1
	v_cmp_ne_u32_e32 vcc, 0, v58
	s_cbranch_vccz .LBB0_596
	ds_read_b128 v[180:183], v143 offset:40960
	ds_read_b128 v[184:187], v143 offset:43264
	ds_read_b128 v[188:191], v143 offset:45568
	ds_read_b128 v[192:195], v143 offset:47872
	ds_read_b128 v[196:199], v143 offset:41024
	ds_read_b128 v[220:223], v143 offset:43328
	ds_read_b128 v[240:243], v143 offset:45632
	ds_read_b128 v[244:247], v143 offset:47936
	s_waitcnt lgkmcnt(7)
	v_mfma_f32_16x16x32_bf16 v[102:105], v[180:183], v[18:21], 0
	ds_read_b128 v[86:89], v143 offset:50176
	s_waitcnt lgkmcnt(7)
	v_mfma_f32_16x16x32_bf16 v[98:101], v[184:187], v[18:21], 0
	ds_read_b128 v[82:85], v143 offset:50240
	s_waitcnt lgkmcnt(7)
	v_mfma_f32_16x16x32_bf16 v[94:97], v[188:191], v[18:21], 0
	ds_read_b128 v[78:81], v143 offset:52480
	s_waitcnt lgkmcnt(7)
	v_mfma_f32_16x16x32_bf16 v[90:93], v[192:195], v[18:21], 0
	ds_read_b128 v[74:77], v143 offset:52544
	s_waitcnt lgkmcnt(7)
	v_mfma_f32_16x16x32_bf16 v[102:105], v[196:199], v[22:25], v[102:105]
	ds_read_b128 v[70:73], v143 offset:54784
	s_waitcnt lgkmcnt(7)
	v_mfma_f32_16x16x32_bf16 v[98:101], v[220:223], v[22:25], v[98:101]
	ds_read_b128 v[66:69], v143 offset:54848
	s_waitcnt lgkmcnt(7)
	v_mfma_f32_16x16x32_bf16 v[94:97], v[240:243], v[22:25], v[94:97]
	ds_read_b128 v[62:65], v143 offset:57088
	s_waitcnt lgkmcnt(7)
	v_mfma_f32_16x16x32_bf16 v[90:93], v[244:247], v[22:25], v[90:93]
	ds_read_b128 v[58:61], v143 offset:57152
	s_cmp_lg_u32 s32, 0
	s_cbranch_scc1 .Lsel_X_defer
	s_add_i32 s10, s13, 64
	s_cmpk_gt_i32 s10, 0x70
	s_cbranch_scc1 .LBB0_597
	v_add_u32_e32 v114, s13, v145
	v_add_u32_e32 v180, 0x7f, v114
	v_add_u32_e32 v181, 0x7e, v114
	v_add_u32_e32 v182, 0x7d, v114
	v_add_u32_e32 v183, 0x7c, v114
	v_add_u32_e32 v184, 0x6f, v114
	v_add_u32_e32 v185, 0x6e, v114
	v_add_u32_e32 v186, 0x6d, v114
	v_add_u32_e32 v187, 0x6c, v114
	v_add_u32_e32 v188, 0x5f, v114
	v_add_u32_e32 v189, 0x5e, v114
	v_add_u32_e32 v190, 0x5d, v114
	v_add_u32_e32 v191, 0x5c, v114
	v_add_u32_e32 v192, 0x4f, v114
	v_add_u32_e32 v193, 0x4e, v114
	v_add_u32_e32 v194, 0x4d, v114
	v_add_u32_e32 v195, 0x4c, v114
	v_med3_i32 v180, v180, 0, v227
	v_med3_i32 v181, v181, 0, v227
	v_med3_i32 v182, v182, 0, v227
	v_med3_i32 v183, v183, 0, v227
	v_med3_i32 v184, v184, 0, v227
	v_med3_i32 v185, v185, 0, v227
	v_med3_i32 v186, v186, 0, v227
	v_med3_i32 v187, v187, 0, v227
	v_med3_i32 v188, v188, 0, v227
	v_med3_i32 v189, v189, 0, v227
	v_med3_i32 v190, v190, 0, v227
	v_med3_i32 v191, v191, 0, v227
	v_med3_i32 v192, v192, 0, v227
	v_med3_i32 v193, v193, 0, v227
	v_med3_i32 v194, v194, 0, v227
	v_med3_i32 v195, v195, 0, v227
	v_lshl_add_u32 v180, v180, 2, s85
	v_lshl_add_u32 v181, v181, 2, s85
	v_lshl_add_u32 v182, v182, 2, s85
	v_lshl_add_u32 v183, v183, 2, s85
	v_lshl_add_u32 v184, v184, 2, s85
	v_lshl_add_u32 v185, v185, 2, s85
	v_lshl_add_u32 v186, v186, 2, s85
	v_lshl_add_u32 v187, v187, 2, s85
	v_lshl_add_u32 v188, v188, 2, s85
	v_lshl_add_u32 v189, v189, 2, s85
	v_lshl_add_u32 v190, v190, 2, s85
	v_lshl_add_u32 v191, v191, 2, s85
	v_lshl_add_u32 v192, v192, 2, s85
	v_lshl_add_u32 v193, v193, 2, s85
	v_lshl_add_u32 v194, v194, 2, s85
	v_lshl_add_u32 v195, v195, 2, s85
	ds_read_b32 v180, v180
	ds_read_b32 v181, v181
	ds_read_b32 v182, v182
	ds_read_b32 v183, v183
	ds_read_b32 v184, v184
	ds_read_b32 v185, v185
	ds_read_b32 v186, v186
	ds_read_b32 v187, v187
	ds_read_b32 v188, v188
	ds_read_b32 v189, v189
	ds_read_b32 v190, v190
	ds_read_b32 v191, v191
	ds_read_b32 v192, v192
	ds_read_b32 v193, v193
	ds_read_b32 v194, v194
	ds_read_b32 v195, v195
	s_waitcnt lgkmcnt(12)
	v_cmp_lt_i32_e32 vcc, 0xffffff80, v114
	s_and_b64 vcc, s[0:1], vcc
	v_fmac_f32_e32 v180, 0x3e38aa3b, v102
	v_cndmask_b32_e32 v102, v228, v180, vcc
	v_cmp_lt_i32_e32 vcc, 0xffffff81, v114
	s_and_b64 vcc, s[0:1], vcc
	v_fmac_f32_e32 v181, 0x3e38aa3b, v103
	v_cndmask_b32_e32 v103, v228, v181, vcc
	v_cmp_lt_i32_e32 vcc, 0xffffff82, v114
	s_and_b64 vcc, s[0:1], vcc
	v_fmac_f32_e32 v182, 0x3e38aa3b, v104
	v_cndmask_b32_e32 v104, v228, v182, vcc
	v_cmp_lt_i32_e32 vcc, 0xffffff83, v114
	s_and_b64 vcc, s[0:1], vcc
	v_fmac_f32_e32 v183, 0x3e38aa3b, v105
	v_cndmask_b32_e32 v105, v228, v183, vcc
	s_waitcnt lgkmcnt(8)
	v_cmp_lt_i32_e32 vcc, 0xffffff90, v114
	s_and_b64 vcc, s[0:1], vcc
	v_fmac_f32_e32 v184, 0x3e38aa3b, v98
	v_cndmask_b32_e32 v98, v228, v184, vcc
	v_cmp_lt_i32_e32 vcc, 0xffffff91, v114
	s_and_b64 vcc, s[0:1], vcc
	v_fmac_f32_e32 v185, 0x3e38aa3b, v99
	v_cndmask_b32_e32 v99, v228, v185, vcc
	v_cmp_lt_i32_e32 vcc, 0xffffff92, v114
	s_and_b64 vcc, s[0:1], vcc
	v_fmac_f32_e32 v186, 0x3e38aa3b, v100
	v_cndmask_b32_e32 v100, v228, v186, vcc
	v_cmp_lt_i32_e32 vcc, 0xffffff93, v114
	s_and_b64 vcc, s[0:1], vcc
	v_fmac_f32_e32 v187, 0x3e38aa3b, v101
	v_cndmask_b32_e32 v101, v228, v187, vcc
	s_waitcnt lgkmcnt(4)
	v_cmp_lt_i32_e32 vcc, 0xffffffa0, v114
	s_and_b64 vcc, s[0:1], vcc
	v_fmac_f32_e32 v188, 0x3e38aa3b, v94
	v_cndmask_b32_e32 v94, v228, v188, vcc
	v_cmp_lt_i32_e32 vcc, 0xffffffa1, v114
	s_and_b64 vcc, s[0:1], vcc
	v_fmac_f32_e32 v189, 0x3e38aa3b, v95
	v_cndmask_b32_e32 v95, v228, v189, vcc
	v_cmp_lt_i32_e32 vcc, 0xffffffa2, v114
	s_and_b64 vcc, s[0:1], vcc
	v_fmac_f32_e32 v190, 0x3e38aa3b, v96
	v_cndmask_b32_e32 v96, v228, v190, vcc
	v_cmp_lt_i32_e32 vcc, 0xffffffa3, v114
	s_and_b64 vcc, s[0:1], vcc
	v_fmac_f32_e32 v191, 0x3e38aa3b, v97
	v_cndmask_b32_e32 v97, v228, v191, vcc
	s_waitcnt lgkmcnt(0)
	v_cmp_lt_i32_e32 vcc, 0xffffffb0, v114
	s_and_b64 vcc, s[0:1], vcc
	v_fmac_f32_e32 v192, 0x3e38aa3b, v90
	v_cndmask_b32_e32 v90, v228, v192, vcc
	v_cmp_lt_i32_e32 vcc, 0xffffffb1, v114
	s_and_b64 vcc, s[0:1], vcc
	v_fmac_f32_e32 v193, 0x3e38aa3b, v91
	v_cndmask_b32_e32 v91, v228, v193, vcc
	v_cmp_lt_i32_e32 vcc, 0xffffffb2, v114
	s_and_b64 vcc, s[0:1], vcc
	v_fmac_f32_e32 v194, 0x3e38aa3b, v92
	v_cndmask_b32_e32 v92, v228, v194, vcc
	v_cmp_lt_i32_e32 vcc, 0xffffffb3, v114
	s_and_b64 vcc, s[0:1], vcc
	v_fmac_f32_e32 v195, 0x3e38aa3b, v93
	v_cndmask_b32_e32 v93, v228, v195, vcc
	s_cbranch_execz .LBB0_598
	v_mov_b32_e32 v114, 1.0
	v_mov_b32_e32 v121, 0
	s_branch .LBB0_599

; #define LBAR() do { asm volatile("s_waitcnt lgkmcnt(0)" ::: "memory"); __builtin_amdgcn_s_barrier(); asm volatile("" ::: "memory"); } while (0)
; #define AT_LOAD(s_, k_, v_) do { k_ = *(const u32x4*)(kg + (size_t)(s_) * 4096); v_ = *(const u32x4*)(vg + (s_) * 64); } while (0)
; #define AT_STORE(sb_, k_, v_) do { *(u32x4*)((sb_) + kdst) = k_; *(u32x2*)((sb_) + vdst) = (u32x2){v_.x, v_.y}; *(u32x2*)((sb_) + vdst + 16) = (u32x2){v_.z, v_.w}; } while (0)
; template <int MODE> ...
;     ...
;         if (st + 1 <= st_hi) AT_STORE(sb1, kb, vb);
;         LBAR();
;         if (st + 1 > st_hi) break;
;         if (st + 3 <= st_hi) AT_LOAD(st + 3, kb, vb);
.Lsel_X_tail:
	s_cmp_lt_u32 s16, s97
	s_cselect_b64 s[0:1], -1, 0
	s_cmp_ge_u32 s16, s97
	s_cbranch_scc1 .LBB0_603
.LBB0_602:
	v_add_u32_e32 v179, 0, v139
	v_add_u32_e32 v179, 0xe800, v179
	s_cmp_lg_u64 s[6:7], 0
	s_cbranch_scc0 .Lsel_xt_nold
	s_waitcnt vmcnt(3)
	ds_write_b128 v141, v[10:13] offset:59392
	s_waitcnt vmcnt(2)
	ds_write2_b64 v179, v[14:15], v[16:17] offset1:2
	s_branch .LBB0_603
.Lsel_xt_nold:
	s_waitcnt vmcnt(1)
	ds_write_b128 v141, v[10:13] offset:59392
	s_waitcnt vmcnt(0)
	ds_write2_b64 v179, v[14:15], v[16:17] offset1:2
.LBB0_603:
	s_waitcnt lgkmcnt(0)
	s_barrier
	s_andn2_b64 vcc, exec, s[0:1]
	s_mov_b64 s[0:1], -1
	s_cbranch_vccnz .LBB0_610
	s_cmp_gt_u32 s14, s97
	s_cbranch_scc1 .LBB0_606
	v_lshl_add_u64 v[248:249], v[112:113], 0, s[38:39]
	v_lshl_add_u64 v[250:251], v[110:111], 0, s[38:39]
	v_add_co_u32_e32 v248, vcc, 0x1a4ba000, v248
	s_nop 1
	v_addc_co_u32_e32 v249, vcc, 0, v249, vcc
	v_add_co_u32_e32 v250, vcc, 0x1a8b4000, v250
	s_nop 1
	v_addc_co_u32_e32 v251, vcc, 0, v251, vcc
	global_load_dwordx4 v[10:13], v[248:249], off offset:2048
	global_load_dwordx4 v[14:17], v[250:251], off offset:2432

; #define AT_LOAD(s_, k_, v_) do { k_ = *(const u32x4*)(kg + (size_t)(s_) * 4096); v_ = *(const u32x4*)(vg + (s_) * 64); } while (0)
; #define AT_COMPUTE(sb_, s_) do { bool sel_ = true; if (MODE == 0) sel_ = (selm >> (s_)) & 1u; \
;         if ((s_) >= my_lo && (MODE == 1 || __ballot(sel_) != 0ull)) attn_step<MODE>(sb_, s_, qf0, qf1, t, p0, sel_, bias, cfar, o, mrun, lrun, koff, voff, q4); } while (0)
; template <int MODE>
; __device__ __forceinline__ void attn_step(const unsigned char* sb, int st, const bf16x8 qf0, const bf16x8 qf1, int t, int p0, bool sel, const float* bias, float cfar, f32x4 (&o)[4], float& mrun, float& lrun,
;                                           int koff, int voff, int q4) {
;     const int key0 = st * 64;
;     f32x4 s[4];
; #pragma unroll
;     for (int kt = 0; kt < 4; ++kt) {
;         const bf16x8 k0 = *(const bf16x8*)(sb + koff + kt * 16 * AKP), k1 = *(const bf16x8*)(sb + koff + kt * 16 * AKP + 64);
;         s[kt] = (f32x4){0.f, 0.f, 0.f, 0.f};
;         s[kt] = __builtin_amdgcn_mfma_f32_16x16x32_bf16(k0, qf0, s[kt], 0, 0, 0); s[kt] = __builtin_amdgcn_mfma_f32_16x16x32_bf16(k1, qf1, s[kt], 0, 0, 0);
;     }
;     const bool far = (p0 - (key0 + 63) >= BIAS_N - 1) && (MODE == 0 || (p0 + 15 - key0 < 512));
;     bf16x8 vfr[4][2];
; #pragma unroll
;     for (int dt = 0; dt < 4; ++dt) { vfr[dt][0] = *(const bf16x8*)(sb + voff + dt * 16 * AKP); vfr[dt][1] = *(const bf16x8*)(sb + voff + dt * 16 * AKP + 64); }
;     float fsc = 1.f, fc = 0.f;
;     if (far) {
;         fc = (MODE == 0 && !sel) ? MASKV : cfar; fsc = (MODE == 0 && !sel) ? 0.f : SC2;
;     } else {
; #pragma unroll
;         for (int kt = 0; kt < 4; ++kt)
; #pragma unroll
;             for (int j = 0; j < 4; ++j) {
;                 const int dist = t - (key0 + kt * 16 + q4 * 4 + j);
;                 const bool v = (dist >= 0) && (MODE == 0 ? sel : (dist < 512));
;                 const int bi = dist < 0 ? 0 : (dist > BIAS_N - 1 ? BIAS_N - 1 : dist);
;                 const float l = s[kt][j] * SC2 + bias[bi];
;                 s[kt][j] = v ? l : MASKV;
;             }
;     }
; template <int MODE> ...
;     ...
;         if (st + 3 <= st_hi) AT_LOAD(st + 3, kb, vb);
;         AT_COMPUTE(sb1, st + 1);
.Lsel_Y_go:
	v_and_b32_e32 v58, 2, v120
	v_cmp_ne_u32_e64 s[0:1], 0, v58
	v_bfe_u32 v58, v120, 1, 1
	v_cmp_ne_u32_e32 vcc, 0, v58
	s_cbranch_vccz .LBB0_611
	ds_read_b128 v[180:183], v143 offset:59392
	ds_read_b128 v[184:187], v143 offset:61696
	ds_read_b128 v[188:191], v143 offset:64000
	ds_read_b128 v[192:195], v144 offset:6912
	ds_read_b128 v[196:199], v143 offset:59456
	ds_read_b128 v[220:223], v143 offset:61760
	ds_read_b128 v[240:243], v143 offset:64064
	ds_read_b128 v[244:247], v144 offset:6976
	s_add_i32 s10, 0, 0xe800
	s_waitcnt lgkmcnt(7)
	v_mfma_f32_16x16x32_bf16 v[102:105], v[180:183], v[18:21], 0
	v_add_u32_e32 v58, 0, v140
	ds_read_b128 v[86:89], v58 offset:59392
	s_waitcnt lgkmcnt(7)
	v_mfma_f32_16x16x32_bf16 v[98:101], v[184:187], v[18:21], 0
	ds_read_b128 v[82:85], v58 offset:59456
	s_waitcnt lgkmcnt(7)
	v_mfma_f32_16x16x32_bf16 v[94:97], v[188:191], v[18:21], 0
	ds_read_b128 v[78:81], v58 offset:61696
	s_waitcnt lgkmcnt(7)
	v_mfma_f32_16x16x32_bf16 v[90:93], v[192:195], v[18:21], 0
	ds_read_b128 v[74:77], v58 offset:61760
	s_waitcnt lgkmcnt(7)
	v_mfma_f32_16x16x32_bf16 v[102:105], v[196:199], v[22:25], v[102:105]
	ds_read_b128 v[70:73], v58 offset:64000
	s_waitcnt lgkmcnt(7)
	v_mfma_f32_16x16x32_bf16 v[98:101], v[220:223], v[22:25], v[98:101]
	ds_read_b128 v[66:69], v58 offset:64064
	s_waitcnt lgkmcnt(7)
	v_mfma_f32_16x16x32_bf16 v[94:97], v[240:243], v[22:25], v[94:97]
	v_add_u32_e32 v58, s10, v140
	ds_read_b128 v[62:65], v58 offset:6912
	s_waitcnt lgkmcnt(7)
	v_mfma_f32_16x16x32_bf16 v[90:93], v[244:247], v[22:25], v[90:93]
	ds_read_b128 v[58:61], v58 offset:6976
	s_cmp_lg_u32 s32, 0
	s_cbranch_scc1 .Lsel_Y_defer
	s_cmpk_gt_i32 s13, 0x70
	s_cbranch_scc1 .LBB0_612
	v_add_u32_e32 v114, s13, v145
	v_add_u32_e32 v180, 63, v114
	v_add_u32_e32 v181, 62, v114
	v_add_u32_e32 v182, 61, v114
	v_add_u32_e32 v183, 60, v114
	v_add_u32_e32 v184, 47, v114
	v_add_u32_e32 v185, 46, v114
	v_add_u32_e32 v186, 45, v114
	v_add_u32_e32 v187, 44, v114
	v_add_u32_e32 v188, 31, v114
	v_add_u32_e32 v189, 30, v114
	v_add_u32_e32 v190, 29, v114
	v_add_u32_e32 v191, 28, v114
	v_add_u32_e32 v192, 15, v114
	v_add_u32_e32 v193, 14, v114
	v_add_u32_e32 v194, 13, v114
	v_add_u32_e32 v195, 12, v114
	v_med3_i32 v180, v180, 0, v227
	v_med3_i32 v181, v181, 0, v227
	v_med3_i32 v182, v182, 0, v227
	v_med3_i32 v183, v183, 0, v227
	v_med3_i32 v184, v184, 0, v227
	v_med3_i32 v185, v185, 0, v227
	v_med3_i32 v186, v186, 0, v227
	v_med3_i32 v187, v187, 0, v227
	v_med3_i32 v188, v188, 0, v227
	v_med3_i32 v189, v189, 0, v227
	v_med3_i32 v190, v190, 0, v227
	v_med3_i32 v191, v191, 0, v227
	v_med3_i32 v192, v192, 0, v227
	v_med3_i32 v193, v193, 0, v227
	v_med3_i32 v194, v194, 0, v227
	v_med3_i32 v195, v195, 0, v227
	v_lshl_add_u32 v180, v180, 2, s85
	v_lshl_add_u32 v181, v181, 2, s85
	v_lshl_add_u32 v182, v182, 2, s85
	v_lshl_add_u32 v183, v183, 2, s85
	v_lshl_add_u32 v184, v184, 2, s85
	v_lshl_add_u32 v185, v185, 2, s85
	v_lshl_add_u32 v186, v186, 2, s85
	v_lshl_add_u32 v187, v187, 2, s85
	v_lshl_add_u32 v188, v188, 2, s85
	v_lshl_add_u32 v189, v189, 2, s85
	v_lshl_add_u32 v190, v190, 2, s85
	v_lshl_add_u32 v191, v191, 2, s85
	v_lshl_add_u32 v192, v192, 2, s85
	v_lshl_add_u32 v193, v193, 2, s85
	v_lshl_add_u32 v194, v194, 2, s85
	v_lshl_add_u32 v195, v195, 2, s85
	ds_read_b32 v180, v180
	ds_read_b32 v181, v181
	ds_read_b32 v182, v182
	ds_read_b32 v183, v183
	ds_read_b32 v184, v184
	ds_read_b32 v185, v185
	ds_read_b32 v186, v186
	ds_read_b32 v187, v187
	ds_read_b32 v188, v188
	ds_read_b32 v189, v189
	ds_read_b32 v190, v190
	ds_read_b32 v191, v191
	ds_read_b32 v192, v192
	ds_read_b32 v193, v193
	ds_read_b32 v194, v194
	ds_read_b32 v195, v195
	s_waitcnt lgkmcnt(12)
	v_cmp_lt_i32_e32 vcc, 0xffffffc0, v114
	s_and_b64 vcc, s[0:1], vcc
	v_fmac_f32_e32 v180, 0x3e38aa3b, v102
	v_cndmask_b32_e32 v102, v228, v180, vcc
	v_cmp_lt_i32_e32 vcc, 0xffffffc1, v114
	s_and_b64 vcc, s[0:1], vcc
	v_fmac_f32_e32 v181, 0x3e38aa3b, v103
	v_cndmask_b32_e32 v103, v228, v181, vcc
	v_cmp_lt_i32_e32 vcc, 0xffffffc2, v114
	s_and_b64 vcc, s[0:1], vcc
	v_fmac_f32_e32 v182, 0x3e38aa3b, v104
	v_cndmask_b32_e32 v104, v228, v182, vcc
	v_cmp_lt_i32_e32 vcc, 0xffffffc3, v114
	s_and_b64 vcc, s[0:1], vcc
	v_fmac_f32_e32 v183, 0x3e38aa3b, v105
	v_cndmask_b32_e32 v105, v228, v183, vcc
	s_waitcnt lgkmcnt(8)
	v_cmp_lt_i32_e32 vcc, 0xffffffd0, v114
	s_and_b64 vcc, s[0:1], vcc
	v_fmac_f32_e32 v184, 0x3e38aa3b, v98
	v_cndmask_b32_e32 v98, v228, v184, vcc
	v_cmp_lt_i32_e32 vcc, 0xffffffd1, v114
	s_and_b64 vcc, s[0:1], vcc
	v_fmac_f32_e32 v185, 0x3e38aa3b, v99
	v_cndmask_b32_e32 v99, v228, v185, vcc
	v_cmp_lt_i32_e32 vcc, 0xffffffd2, v114
	s_and_b64 vcc, s[0:1], vcc
	v_fmac_f32_e32 v186, 0x3e38aa3b, v100
	v_cndmask_b32_e32 v100, v228, v186, vcc
	v_cmp_lt_i32_e32 vcc, 0xffffffd3, v114
	s_and_b64 vcc, s[0:1], vcc
	v_fmac_f32_e32 v187, 0x3e38aa3b, v101
	v_cndmask_b32_e32 v101, v228, v187, vcc
	s_waitcnt lgkmcnt(4)
	v_cmp_lt_i32_e32 vcc, 0xffffffe0, v114
	s_and_b64 vcc, s[0:1], vcc
	v_fmac_f32_e32 v188, 0x3e38aa3b, v94
	v_cndmask_b32_e32 v94, v228, v188, vcc
	v_cmp_lt_i32_e32 vcc, 0xffffffe1, v114
	s_and_b64 vcc, s[0:1], vcc
	v_fmac_f32_e32 v189, 0x3e38aa3b, v95
	v_cndmask_b32_e32 v95, v228, v189, vcc
	v_cmp_lt_i32_e32 vcc, 0xffffffe2, v114
	s_and_b64 vcc, s[0:1], vcc
	v_fmac_f32_e32 v190, 0x3e38aa3b, v96
	v_cndmask_b32_e32 v96, v228, v190, vcc
	v_cmp_lt_i32_e32 vcc, 0xffffffe3, v114
	s_and_b64 vcc, s[0:1], vcc
	v_fmac_f32_e32 v191, 0x3e38aa3b, v97
	v_cndmask_b32_e32 v97, v228, v191, vcc
	s_waitcnt lgkmcnt(0)
	v_cmp_lt_i32_e32 vcc, 0xfffffff0, v114
	s_and_b64 vcc, s[0:1], vcc
	v_fmac_f32_e32 v192, 0x3e38aa3b, v90
	v_cndmask_b32_e32 v90, v228, v192, vcc
	v_cmp_lt_i32_e32 vcc, 0xfffffff1, v114
	s_and_b64 vcc, s[0:1], vcc
	v_fmac_f32_e32 v193, 0x3e38aa3b, v91
	v_cndmask_b32_e32 v91, v228, v193, vcc
	v_cmp_lt_i32_e32 vcc, 0xfffffff2, v114
	s_and_b64 vcc, s[0:1], vcc
	v_fmac_f32_e32 v194, 0x3e38aa3b, v92
	v_cndmask_b32_e32 v92, v228, v194, vcc
	v_cmp_lt_i32_e32 vcc, 0xfffffff3, v114
	s_and_b64 vcc, s[0:1], vcc
	v_fmac_f32_e32 v195, 0x3e38aa3b, v93
	v_cndmask_b32_e32 v93, v228, v195, vcc
	s_cbranch_execz .LBB0_613
	v_mov_b32_e32 v114, 1.0
	v_mov_b32_e32 v120, 0
	s_branch .LBB0_614

; __device__ __forceinline__ bf16x8 pack_p(const float* a, const float* b) { u32x4 w; w.x = cvtpk(a[0], a[1]); w.y = cvtpk(a[2], a[3]); w.z = cvtpk(b[0], b[1]); w.w = cvtpk(b[2], b[3]); return __builtin_bit_cast(bf16x8, w); }
; #define AT_STORE(sb_, k_, v_) do { *(u32x4*)((sb_) + kdst) = k_; *(u32x2*)((sb_) + vdst) = (u32x2){v_.x, v_.y}; *(u32x2*)((sb_) + vdst + 16) = (u32x2){v_.z, v_.w}; } while (0)
; template <int MODE>
; __device__ __forceinline__ void attn_step(const unsigned char* sb, int st, const bf16x8 qf0, const bf16x8 qf1, int t, int p0, bool sel, const float* bias, float cfar, f32x4 (&o)[4], float& mrun, float& lrun,
;                                           int koff, int voff, int q4) {
;     ...
;     f32x4 ps4 = {0.f, 0.f, 0.f, 0.f};
;     const float foff = fc - mnew;
; #pragma unroll
;     for (int kt = 0; kt < 4; ++kt) {
;         s[kt] = s[kt] * fsc + foff;
; #pragma unroll
;         for (int j = 0; j < 4; ++j) s[kt][j] = __builtin_amdgcn_exp2f(s[kt][j]);
;         ps4 += s[kt];
;     }
;     const float ps = (ps4.x + ps4.y) + (ps4.z + ps4.w);
;     if (__ballot(mnew != mrun) != 0ull) {
;         const float alpha = __builtin_amdgcn_exp2f(mrun - mnew);
;         lrun *= alpha;
; #pragma unroll
;         for (int dt = 0; dt < 4; ++dt) o[dt] *= alpha;
;     }
;     lrun += ps; mrun = mnew;
;     float pa[4][4];
; #pragma unroll
;     for (int kt = 0; kt < 4; ++kt)
; #pragma unroll
;         for (int j = 0; j < 4; ++j) pa[kt][j] = s[kt][j];
;     const bf16x8 pf0 = pack_p(pa[0], pa[1]), pf1 = pack_p(pa[2], pa[3]);
; #pragma unroll
;     for (int dt = 0; dt < 4; ++dt) {
;         o[dt] = __builtin_amdgcn_mfma_f32_16x16x32_bf16(vfr[dt][0], pf0, o[dt], 0, 0, 0); o[dt] = __builtin_amdgcn_mfma_f32_16x16x32_bf16(vfr[dt][1], pf1, o[dt], 0, 0, 0);
;     }
; template <int MODE> ...
;     ...
;         if (st + 2 <= st_hi) AT_STORE(sb0, ka, va);
.LBB0_616:
	v_sub_f32_e32 v120, v120, v118
	v_pk_fma_f32 v[104:105], v[104:105], v[114:115], v[120:121] op_sel_hi:[1,0,0]
	v_pk_fma_f32 v[102:103], v[102:103], v[114:115], v[120:121] op_sel_hi:[1,0,0]
	v_exp_f32_e32 v104, v104
	v_exp_f32_e32 v102, v102
	v_exp_f32_e32 v103, v103
	v_exp_f32_e32 v105, v105
	v_pk_fma_f32 v[100:101], v[100:101], v[114:115], v[120:121] op_sel_hi:[1,0,0]
	v_pk_fma_f32 v[98:99], v[98:99], v[114:115], v[120:121] op_sel_hi:[1,0,0]
	v_exp_f32_e32 v100, v100
	v_exp_f32_e32 v98, v98
	v_exp_f32_e32 v99, v99
	v_exp_f32_e32 v101, v101
	v_pk_fma_f32 v[96:97], v[96:97], v[114:115], v[120:121] op_sel_hi:[1,0,0]
	v_pk_fma_f32 v[94:95], v[94:95], v[114:115], v[120:121] op_sel_hi:[1,0,0]
	v_exp_f32_e32 v96, v96
	v_exp_f32_e32 v94, v94
	v_exp_f32_e32 v95, v95
	v_exp_f32_e32 v97, v97
	v_pk_fma_f32 v[92:93], v[92:93], v[114:115], v[120:121] op_sel_hi:[1,0,0]
	v_pk_fma_f32 v[90:91], v[90:91], v[114:115], v[120:121] op_sel_hi:[1,0,0]
	v_exp_f32_e32 v146, v92
	v_exp_f32_e32 v120, v90
	v_exp_f32_e32 v121, v91
	v_exp_f32_e32 v147, v93
	v_pk_add_f32 v[132:133], v[102:103], 0 op_sel_hi:[1,0]
	v_pk_add_f32 v[134:135], v[104:105], 0 op_sel_hi:[1,0]
	v_pk_add_f32 v[132:133], v[98:99], v[132:133]
	v_pk_add_f32 v[134:135], v[100:101], v[134:135]
	v_pk_add_f32 v[132:133], v[94:95], v[132:133]
	v_pk_add_f32 v[134:135], v[96:97], v[134:135]
	v_pk_add_f32 v[92:93], v[120:121], v[132:133]
	v_pk_add_f32 v[90:91], v[146:147], v[134:135]
	v_cvt_pk_bf16_f32 v94, v94, v95
	v_pk_mov_b32 v[132:133], v[92:93], v[90:91] op_sel:[1,0]
	v_mov_b32_e32 v93, v91
	v_pk_add_f32 v[90:91], v[132:133], v[92:93]
	v_cvt_pk_bf16_f32 v92, v98, v99
	v_add_f32_e32 v90, v90, v91
	v_add_f32_e32 v117, v90, v117
	v_cvt_pk_bf16_f32 v90, v102, v103
	v_cvt_pk_bf16_f32 v91, v104, v105
	v_cvt_pk_bf16_f32 v93, v100, v101
	v_cvt_pk_bf16_f32 v95, v96, v97
	v_cvt_pk_bf16_f32 v96, v120, v121
	s_waitcnt lgkmcnt(0)
	v_mfma_f32_16x16x32_bf16 v[46:49], v[86:89], v[90:93], v[46:49]
	v_cvt_pk_bf16_f32 v97, v146, v147
	v_mfma_f32_16x16x32_bf16 v[42:45], v[78:81], v[90:93], v[42:45]
	v_mfma_f32_16x16x32_bf16 v[50:53], v[70:73], v[90:93], v[50:53]
	v_mfma_f32_16x16x32_bf16 v[54:57], v[62:65], v[90:93], v[54:57]
	v_mfma_f32_16x16x32_bf16 v[46:49], v[82:85], v[94:97], v[46:49]
	v_mfma_f32_16x16x32_bf16 v[42:45], v[74:77], v[94:97], v[42:45]
	v_mfma_f32_16x16x32_bf16 v[50:53], v[66:69], v[94:97], v[50:53]
	v_mfma_f32_16x16x32_bf16 v[54:57], v[58:61], v[94:97], v[54:57]
.Lsel_Y_tail:
	s_andn2_b64 vcc, exec, s[6:7]
	s_cbranch_vccnz .LBB0_589
.LBB0_617:
	s_cmp_gt_u32 s14, s97
	s_cbranch_scc1 .Lsel_yt_nold
	s_waitcnt vmcnt(3)
	ds_write_b128 v141, v[2:5] offset:40960
	s_waitcnt vmcnt(2)
	ds_write2_b64 v142, v[6:7], v[8:9] offset0:128 offset1:130
	s_branch .LBB0_589

; template <int MODE>
; __device__ __forceinline__ void attn_step(const unsigned char* sb, int st, const bf16x8 qf0, const bf16x8 qf1, int t, int p0, bool sel, const float* bias, float cfar, f32x4 (&o)[4], float& mrun, float& lrun,
;                                           int koff, int voff, int q4) {
;     ...
;     const bool far = (p0 - (key0 + 63) >= BIAS_N - 1) && (MODE == 0 || (p0 + 15 - key0 < 512));
;     bf16x8 vfr[4][2];
; #pragma unroll
;     for (int dt = 0; dt < 4; ++dt) { vfr[dt][0] = *(const bf16x8*)(sb + voff + dt * 16 * AKP); vfr[dt][1] = *(const bf16x8*)(sb + voff + dt * 16 * AKP + 64); }
;     float fsc = 1.f, fc = 0.f;
;     if (far) {
;         fc = (MODE == 0 && !sel) ? MASKV : cfar; fsc = (MODE == 0 && !sel) ? 0.f : SC2;
;     } else {
; #pragma unroll
;         for (int kt = 0; kt < 4; ++kt)
; #pragma unroll
;             for (int j = 0; j < 4; ++j) {
;                 const int dist = t - (key0 + kt * 16 + q4 * 4 + j);
;                 const bool v = (dist >= 0) && (MODE == 0 ? sel : (dist < 512));
;                 const int bi = dist < 0 ? 0 : (dist > BIAS_N - 1 ? BIAS_N - 1 : dist);
;                 const float l = s[kt][j] * SC2 + bias[bi];
;                 s[kt][j] = v ? l : MASKV;
;             }
;     }
.Lsel_X_defer:
	s_mov_b32 s10, 1
	v_writelane_b32 v255, s10, 60
	s_branch .Lsel_X_tail
.Lsel_Y_defer:
	s_mov_b32 s10, 2
	v_writelane_b32 v255, s10, 60
	s_branch .Lsel_Y_tail
.Lsel_BdX:
	s_add_i32 s10, s14, -3
	v_bfe_u32 v179, v115, s10, 1
	v_cmp_ne_u32_e64 s[0:1], 0, v179
	s_add_i32 s10, s13, 64
	s_cmpk_gt_i32 s10, 0x70
	s_cbranch_scc1 .Lsel_BdX_far
	v_add_u32_e32 v114, s13, v145
	v_add_u32_e32 v180, 0x7f, v114
	v_add_u32_e32 v181, 0x7e, v114
	v_add_u32_e32 v182, 0x7d, v114
	v_add_u32_e32 v183, 0x7c, v114
	v_add_u32_e32 v184, 0x6f, v114
	v_add_u32_e32 v185, 0x6e, v114
	v_add_u32_e32 v186, 0x6d, v114
	v_add_u32_e32 v187, 0x6c, v114
	v_add_u32_e32 v188, 0x5f, v114
	v_add_u32_e32 v189, 0x5e, v114
	v_add_u32_e32 v190, 0x5d, v114
	v_add_u32_e32 v191, 0x5c, v114
	v_add_u32_e32 v192, 0x4f, v114
	v_add_u32_e32 v193, 0x4e, v114
	v_add_u32_e32 v194, 0x4d, v114
	v_add_u32_e32 v195, 0x4c, v114
	v_med3_i32 v180, v180, 0, v227
	v_med3_i32 v181, v181, 0, v227
	v_med3_i32 v182, v182, 0, v227
	v_med3_i32 v183, v183, 0, v227
	v_med3_i32 v184, v184, 0, v227
	v_med3_i32 v185, v185, 0, v227
	v_med3_i32 v186, v186, 0, v227
	v_med3_i32 v187, v187, 0, v227
	v_med3_i32 v188, v188, 0, v227
	v_med3_i32 v189, v189, 0, v227
	v_med3_i32 v190, v190, 0, v227
	v_med3_i32 v191, v191, 0, v227
	v_med3_i32 v192, v192, 0, v227
	v_med3_i32 v193, v193, 0, v227
	v_med3_i32 v194, v194, 0, v227
	v_med3_i32 v195, v195, 0, v227
	v_lshl_add_u32 v180, v180, 2, s85
	v_lshl_add_u32 v181, v181, 2, s85
	v_lshl_add_u32 v182, v182, 2, s85
	v_lshl_add_u32 v183, v183, 2, s85
	v_lshl_add_u32 v184, v184, 2, s85
	v_lshl_add_u32 v185, v185, 2, s85
	v_lshl_add_u32 v186, v186, 2, s85
	v_lshl_add_u32 v187, v187, 2, s85
	v_lshl_add_u32 v188, v188, 2, s85
	v_lshl_add_u32 v189, v189, 2, s85
	v_lshl_add_u32 v190, v190, 2, s85
	v_lshl_add_u32 v191, v191, 2, s85
	v_lshl_add_u32 v192, v192, 2, s85
	v_lshl_add_u32 v193, v193, 2, s85
	v_lshl_add_u32 v194, v194, 2, s85
	v_lshl_add_u32 v195, v195, 2, s85
	ds_read_b32 v180, v180
	ds_read_b32 v181, v181
	ds_read_b32 v182, v182
	ds_read_b32 v183, v183
	ds_read_b32 v184, v184
	ds_read_b32 v185, v185
	ds_read_b32 v186, v186
	ds_read_b32 v187, v187
	ds_read_b32 v188, v188
	ds_read_b32 v189, v189
	ds_read_b32 v190, v190
	ds_read_b32 v191, v191
	ds_read_b32 v192, v192
	ds_read_b32 v193, v193
	ds_read_b32 v194, v194
	ds_read_b32 v195, v195
	s_waitcnt lgkmcnt(12)
	v_cmp_lt_i32_e32 vcc, 0xffffff80, v114
	s_and_b64 vcc, s[0:1], vcc
	v_fmac_f32_e32 v180, 0x3e38aa3b, v102
	v_cndmask_b32_e32 v102, v228, v180, vcc
	v_cmp_lt_i32_e32 vcc, 0xffffff81, v114
	s_and_b64 vcc, s[0:1], vcc
	v_fmac_f32_e32 v181, 0x3e38aa3b, v103
	v_cndmask_b32_e32 v103, v228, v181, vcc
	v_cmp_lt_i32_e32 vcc, 0xffffff82, v114
	s_and_b64 vcc, s[0:1], vcc
	v_fmac_f32_e32 v182, 0x3e38aa3b, v104
	v_cndmask_b32_e32 v104, v228, v182, vcc
	v_cmp_lt_i32_e32 vcc, 0xffffff83, v114
	s_and_b64 vcc, s[0:1], vcc
	v_fmac_f32_e32 v183, 0x3e38aa3b, v105
	v_cndmask_b32_e32 v105, v228, v183, vcc
	s_waitcnt lgkmcnt(8)
	v_cmp_lt_i32_e32 vcc, 0xffffff90, v114
	s_and_b64 vcc, s[0:1], vcc
	v_fmac_f32_e32 v184, 0x3e38aa3b, v98
	v_cndmask_b32_e32 v98, v228, v184, vcc
	v_cmp_lt_i32_e32 vcc, 0xffffff91, v114
	s_and_b64 vcc, s[0:1], vcc
	v_fmac_f32_e32 v185, 0x3e38aa3b, v99
	v_cndmask_b32_e32 v99, v228, v185, vcc
	v_cmp_lt_i32_e32 vcc, 0xffffff92, v114
	s_and_b64 vcc, s[0:1], vcc
	v_fmac_f32_e32 v186, 0x3e38aa3b, v100
	v_cndmask_b32_e32 v100, v228, v186, vcc
	v_cmp_lt_i32_e32 vcc, 0xffffff93, v114
	s_and_b64 vcc, s[0:1], vcc
	v_fmac_f32_e32 v187, 0x3e38aa3b, v101
	v_cndmask_b32_e32 v101, v228, v187, vcc
	s_waitcnt lgkmcnt(4)
	v_cmp_lt_i32_e32 vcc, 0xffffffa0, v114
	s_and_b64 vcc, s[0:1], vcc
	v_fmac_f32_e32 v188, 0x3e38aa3b, v94
	v_cndmask_b32_e32 v94, v228, v188, vcc
	v_cmp_lt_i32_e32 vcc, 0xffffffa1, v114
	s_and_b64 vcc, s[0:1], vcc
	v_fmac_f32_e32 v189, 0x3e38aa3b, v95
	v_cndmask_b32_e32 v95, v228, v189, vcc
	v_cmp_lt_i32_e32 vcc, 0xffffffa2, v114
	s_and_b64 vcc, s[0:1], vcc
	v_fmac_f32_e32 v190, 0x3e38aa3b, v96
	v_cndmask_b32_e32 v96, v228, v190, vcc
	v_cmp_lt_i32_e32 vcc, 0xffffffa3, v114
	s_and_b64 vcc, s[0:1], vcc
	v_fmac_f32_e32 v191, 0x3e38aa3b, v97
	v_cndmask_b32_e32 v97, v228, v191, vcc
	s_waitcnt lgkmcnt(0)
	v_cmp_lt_i32_e32 vcc, 0xffffffb0, v114
	s_and_b64 vcc, s[0:1], vcc
	v_fmac_f32_e32 v192, 0x3e38aa3b, v90
	v_cndmask_b32_e32 v90, v228, v192, vcc
	v_cmp_lt_i32_e32 vcc, 0xffffffb1, v114
	s_and_b64 vcc, s[0:1], vcc
	v_fmac_f32_e32 v193, 0x3e38aa3b, v91
	v_cndmask_b32_e32 v91, v228, v193, vcc
	v_cmp_lt_i32_e32 vcc, 0xffffffb2, v114
	s_and_b64 vcc, s[0:1], vcc
	v_fmac_f32_e32 v194, 0x3e38aa3b, v92
	v_cndmask_b32_e32 v92, v228, v194, vcc
	v_cmp_lt_i32_e32 vcc, 0xffffffb3, v114
	s_and_b64 vcc, s[0:1], vcc
	v_fmac_f32_e32 v195, 0x3e38aa3b, v93
	v_cndmask_b32_e32 v93, v228, v195, vcc
	v_mov_b32_e32 v114, 1.0
	v_mov_b32_e32 v121, 0
	s_branch .Lsel_BdX_common

; __device__ __forceinline__ bf16x8 pack_p(const float* a, const float* b) { u32x4 w; w.x = cvtpk(a[0], a[1]); w.y = cvtpk(a[2], a[3]); w.z = cvtpk(b[0], b[1]); w.w = cvtpk(b[2], b[3]); return __builtin_bit_cast(bf16x8, w); }
; template <int MODE>
; __device__ __forceinline__ void attn_step(const unsigned char* sb, int st, const bf16x8 qf0, const bf16x8 qf1, int t, int p0, bool sel, const float* bias, float cfar, f32x4 (&o)[4], float& mrun, float& lrun,
;                                           int koff, int voff, int q4) {
;     ...
;     f32x4 ps4 = {0.f, 0.f, 0.f, 0.f};
;     const float foff = fc - mnew;
; #pragma unroll
;     for (int kt = 0; kt < 4; ++kt) {
;         s[kt] = s[kt] * fsc + foff;
; #pragma unroll
;         for (int j = 0; j < 4; ++j) s[kt][j] = __builtin_amdgcn_exp2f(s[kt][j]);
;         ps4 += s[kt];
;     }
;     const float ps = (ps4.x + ps4.y) + (ps4.z + ps4.w);
;     if (__ballot(mnew != mrun) != 0ull) {
;         const float alpha = __builtin_amdgcn_exp2f(mrun - mnew);
;         lrun *= alpha;
; #pragma unroll
;         for (int dt = 0; dt < 4; ++dt) o[dt] *= alpha;
;     }
;     lrun += ps; mrun = mnew;
;     float pa[4][4];
; #pragma unroll
;     for (int kt = 0; kt < 4; ++kt)
; #pragma unroll
;         for (int j = 0; j < 4; ++j) pa[kt][j] = s[kt][j];
;     const bf16x8 pf0 = pack_p(pa[0], pa[1]), pf1 = pack_p(pa[2], pa[3]);
; #pragma unroll
;     for (int dt = 0; dt < 4; ++dt) {
;         o[dt] = __builtin_amdgcn_mfma_f32_16x16x32_bf16(vfr[dt][0], pf0, o[dt], 0, 0, 0); o[dt] = __builtin_amdgcn_mfma_f32_16x16x32_bf16(vfr[dt][1], pf1, o[dt], 0, 0, 0);
;     }
.Lsel_BdX_601:
	v_sub_f32_e32 v118, v121, v119
	v_pk_fma_f32 v[104:105], v[104:105], v[114:115], v[118:119] op_sel_hi:[1,0,0]
	v_pk_fma_f32 v[102:103], v[102:103], v[114:115], v[118:119] op_sel_hi:[1,0,0]
	v_exp_f32_e32 v104, v104
	v_exp_f32_e32 v102, v102
	v_exp_f32_e32 v103, v103
	v_exp_f32_e32 v105, v105
	v_pk_fma_f32 v[100:101], v[100:101], v[114:115], v[118:119] op_sel_hi:[1,0,0]
	v_pk_fma_f32 v[98:99], v[98:99], v[114:115], v[118:119] op_sel_hi:[1,0,0]
	v_exp_f32_e32 v100, v100
	v_exp_f32_e32 v98, v98
	v_exp_f32_e32 v99, v99
	v_exp_f32_e32 v101, v101
	v_pk_fma_f32 v[96:97], v[96:97], v[114:115], v[118:119] op_sel_hi:[1,0,0]
	v_pk_fma_f32 v[94:95], v[94:95], v[114:115], v[118:119] op_sel_hi:[1,0,0]
	v_exp_f32_e32 v96, v96
	v_exp_f32_e32 v94, v94
	v_exp_f32_e32 v95, v95
	v_exp_f32_e32 v97, v97
	v_pk_fma_f32 v[92:93], v[92:93], v[114:115], v[118:119] op_sel_hi:[1,0,0]
	v_pk_fma_f32 v[90:91], v[90:91], v[114:115], v[118:119] op_sel_hi:[1,0,0]
	v_exp_f32_e32 v148, v92
	v_exp_f32_e32 v146, v90
	v_exp_f32_e32 v147, v91
	v_exp_f32_e32 v149, v93
	v_pk_add_f32 v[132:133], v[102:103], 0 op_sel_hi:[1,0]
	v_pk_add_f32 v[134:135], v[104:105], 0 op_sel_hi:[1,0]
	v_pk_add_f32 v[132:133], v[98:99], v[132:133]
	v_pk_add_f32 v[134:135], v[100:101], v[134:135]
	v_pk_add_f32 v[132:133], v[94:95], v[132:133]
	v_pk_add_f32 v[134:135], v[96:97], v[134:135]
	v_pk_add_f32 v[92:93], v[146:147], v[132:133]
	v_pk_add_f32 v[90:91], v[148:149], v[134:135]
	v_cvt_pk_bf16_f32 v94, v94, v95
	v_pk_mov_b32 v[132:133], v[92:93], v[90:91] op_sel:[1,0]
	v_mov_b32_e32 v93, v91
	v_pk_add_f32 v[90:91], v[132:133], v[92:93]
	v_cvt_pk_bf16_f32 v92, v98, v99
	v_add_f32_e32 v90, v90, v91
	v_add_f32_e32 v117, v90, v117
	v_cvt_pk_bf16_f32 v90, v102, v103
	v_cvt_pk_bf16_f32 v91, v104, v105
	v_cvt_pk_bf16_f32 v93, v100, v101
	v_cvt_pk_bf16_f32 v95, v96, v97
	v_cvt_pk_bf16_f32 v96, v146, v147
	s_waitcnt lgkmcnt(0)
	v_mfma_f32_16x16x32_bf16 v[46:49], v[86:89], v[90:93], v[46:49]
	v_cvt_pk_bf16_f32 v97, v148, v149
	v_mfma_f32_16x16x32_bf16 v[42:45], v[78:81], v[90:93], v[42:45]
	v_mfma_f32_16x16x32_bf16 v[50:53], v[70:73], v[90:93], v[50:53]
	v_mfma_f32_16x16x32_bf16 v[54:57], v[62:65], v[90:93], v[54:57]
	v_mfma_f32_16x16x32_bf16 v[46:49], v[82:85], v[94:97], v[46:49]
	v_mfma_f32_16x16x32_bf16 v[42:45], v[74:77], v[94:97], v[42:45]
	v_mfma_f32_16x16x32_bf16 v[50:53], v[66:69], v[94:97], v[50:53]
	v_mfma_f32_16x16x32_bf16 v[54:57], v[58:61], v[94:97], v[54:57]
	s_mov_b32 s10, 0
	v_writelane_b32 v255, s10, 60
	s_nop 1
	v_readlane_b32 s10, v255, 61
	s_nop 3
	s_cmp_eq_u32 s10, 1
	s_cbranch_scc1 .Lsel_exit_go
	s_branch .Lsel_Y_go
; template <int MODE>
; __device__ __forceinline__ void attn_step(const unsigned char* sb, int st, const bf16x8 qf0, const bf16x8 qf1, int t, int p0, bool sel, const float* bias, float cfar, f32x4 (&o)[4], float& mrun, float& lrun,
;                                           int koff, int voff, int q4) {
;     ...
;     const bool far = (p0 - (key0 + 63) >= BIAS_N - 1) && (MODE == 0 || (p0 + 15 - key0 < 512));
;     bf16x8 vfr[4][2];
; #pragma unroll
;     for (int dt = 0; dt < 4; ++dt) { vfr[dt][0] = *(const bf16x8*)(sb + voff + dt * 16 * AKP); vfr[dt][1] = *(const bf16x8*)(sb + voff + dt * 16 * AKP + 64); }
;     float fsc = 1.f, fc = 0.f;
;     if (far) {
;         fc = (MODE == 0 && !sel) ? MASKV : cfar; fsc = (MODE == 0 && !sel) ? 0.f : SC2;
;     } else {
; #pragma unroll
;         for (int kt = 0; kt < 4; ++kt)
; #pragma unroll
;             for (int j = 0; j < 4; ++j) {
;                 const int dist = t - (key0 + kt * 16 + q4 * 4 + j);
;                 const bool v = (dist >= 0) && (MODE == 0 ? sel : (dist < 512));
;                 const int bi = dist < 0 ? 0 : (dist > BIAS_N - 1 ? BIAS_N - 1 : dist);
;                 const float l = s[kt][j] * SC2 + bias[bi];
;                 s[kt][j] = v ? l : MASKV;
;             }
;     }
.Lsel_BdY:
	s_add_i32 s10, s14, -4
	v_bfe_u32 v179, v115, s10, 1
	v_cmp_ne_u32_e64 s[0:1], 0, v179
	s_add_i32 s10, s13, 0x80
	s_cmpk_gt_i32 s10, 0x70
	s_cbranch_scc1 .Lsel_BdY_far
	v_add_u32_e32 v114, s10, v145
	v_add_u32_e32 v180, 63, v114
	v_add_u32_e32 v181, 62, v114
	v_add_u32_e32 v182, 61, v114
	v_add_u32_e32 v183, 60, v114
	v_add_u32_e32 v184, 47, v114
	v_add_u32_e32 v185, 46, v114
	v_add_u32_e32 v186, 45, v114
	v_add_u32_e32 v187, 44, v114
	v_add_u32_e32 v188, 31, v114
	v_add_u32_e32 v189, 30, v114
	v_add_u32_e32 v190, 29, v114
	v_add_u32_e32 v191, 28, v114
	v_add_u32_e32 v192, 15, v114
	v_add_u32_e32 v193, 14, v114
	v_add_u32_e32 v194, 13, v114
	v_add_u32_e32 v195, 12, v114
	v_med3_i32 v180, v180, 0, v227
	v_med3_i32 v181, v181, 0, v227
	v_med3_i32 v182, v182, 0, v227
	v_med3_i32 v183, v183, 0, v227
	v_med3_i32 v184, v184, 0, v227
	v_med3_i32 v185, v185, 0, v227
	v_med3_i32 v186, v186, 0, v227
	v_med3_i32 v187, v187, 0, v227
	v_med3_i32 v188, v188, 0, v227
	v_med3_i32 v189, v189, 0, v227
	v_med3_i32 v190, v190, 0, v227
	v_med3_i32 v191, v191, 0, v227
	v_med3_i32 v192, v192, 0, v227
	v_med3_i32 v193, v193, 0, v227
	v_med3_i32 v194, v194, 0, v227
	v_med3_i32 v195, v195, 0, v227
	v_lshl_add_u32 v180, v180, 2, s85
	v_lshl_add_u32 v181, v181, 2, s85
	v_lshl_add_u32 v182, v182, 2, s85
	v_lshl_add_u32 v183, v183, 2, s85
	v_lshl_add_u32 v184, v184, 2, s85
	v_lshl_add_u32 v185, v185, 2, s85
	v_lshl_add_u32 v186, v186, 2, s85
	v_lshl_add_u32 v187, v187, 2, s85
	v_lshl_add_u32 v188, v188, 2, s85
	v_lshl_add_u32 v189, v189, 2, s85
	v_lshl_add_u32 v190, v190, 2, s85
	v_lshl_add_u32 v191, v191, 2, s85
	v_lshl_add_u32 v192, v192, 2, s85
	v_lshl_add_u32 v193, v193, 2, s85
	v_lshl_add_u32 v194, v194, 2, s85
	v_lshl_add_u32 v195, v195, 2, s85
	ds_read_b32 v180, v180
	ds_read_b32 v181, v181
	ds_read_b32 v182, v182
	ds_read_b32 v183, v183
	ds_read_b32 v184, v184
	ds_read_b32 v185, v185
	ds_read_b32 v186, v186
	ds_read_b32 v187, v187
	ds_read_b32 v188, v188
	ds_read_b32 v189, v189
	ds_read_b32 v190, v190
	ds_read_b32 v191, v191
	ds_read_b32 v192, v192
	ds_read_b32 v193, v193
	ds_read_b32 v194, v194
	ds_read_b32 v195, v195
	s_waitcnt lgkmcnt(12)
	v_cmp_lt_i32_e32 vcc, 0xffffffc0, v114
	s_and_b64 vcc, s[0:1], vcc
	v_fmac_f32_e32 v180, 0x3e38aa3b, v102
	v_cndmask_b32_e32 v102, v228, v180, vcc
	v_cmp_lt_i32_e32 vcc, 0xffffffc1, v114
	s_and_b64 vcc, s[0:1], vcc
	v_fmac_f32_e32 v181, 0x3e38aa3b, v103
	v_cndmask_b32_e32 v103, v228, v181, vcc
	v_cmp_lt_i32_e32 vcc, 0xffffffc2, v114
	s_and_b64 vcc, s[0:1], vcc
	v_fmac_f32_e32 v182, 0x3e38aa3b, v104
	v_cndmask_b32_e32 v104, v228, v182, vcc
	v_cmp_lt_i32_e32 vcc, 0xffffffc3, v114
	s_and_b64 vcc, s[0:1], vcc
	v_fmac_f32_e32 v183, 0x3e38aa3b, v105
	v_cndmask_b32_e32 v105, v228, v183, vcc
	s_waitcnt lgkmcnt(8)
	v_cmp_lt_i32_e32 vcc, 0xffffffd0, v114
	s_and_b64 vcc, s[0:1], vcc
	v_fmac_f32_e32 v184, 0x3e38aa3b, v98
	v_cndmask_b32_e32 v98, v228, v184, vcc
	v_cmp_lt_i32_e32 vcc, 0xffffffd1, v114
	s_and_b64 vcc, s[0:1], vcc
	v_fmac_f32_e32 v185, 0x3e38aa3b, v99
	v_cndmask_b32_e32 v99, v228, v185, vcc
	v_cmp_lt_i32_e32 vcc, 0xffffffd2, v114
	s_and_b64 vcc, s[0:1], vcc
	v_fmac_f32_e32 v186, 0x3e38aa3b, v100
	v_cndmask_b32_e32 v100, v228, v186, vcc
	v_cmp_lt_i32_e32 vcc, 0xffffffd3, v114
	s_and_b64 vcc, s[0:1], vcc
	v_fmac_f32_e32 v187, 0x3e38aa3b, v101
	v_cndmask_b32_e32 v101, v228, v187, vcc
	s_waitcnt lgkmcnt(4)
	v_cmp_lt_i32_e32 vcc, 0xffffffe0, v114
	s_and_b64 vcc, s[0:1], vcc
	v_fmac_f32_e32 v188, 0x3e38aa3b, v94
	v_cndmask_b32_e32 v94, v228, v188, vcc
	v_cmp_lt_i32_e32 vcc, 0xffffffe1, v114
	s_and_b64 vcc, s[0:1], vcc
	v_fmac_f32_e32 v189, 0x3e38aa3b, v95
	v_cndmask_b32_e32 v95, v228, v189, vcc
	v_cmp_lt_i32_e32 vcc, 0xffffffe2, v114
	s_and_b64 vcc, s[0:1], vcc
	v_fmac_f32_e32 v190, 0x3e38aa3b, v96
	v_cndmask_b32_e32 v96, v228, v190, vcc
	v_cmp_lt_i32_e32 vcc, 0xffffffe3, v114
	s_and_b64 vcc, s[0:1], vcc
	v_fmac_f32_e32 v191, 0x3e38aa3b, v97
	v_cndmask_b32_e32 v97, v228, v191, vcc
	s_waitcnt lgkmcnt(0)
	v_cmp_lt_i32_e32 vcc, 0xfffffff0, v114
	s_and_b64 vcc, s[0:1], vcc
	v_fmac_f32_e32 v192, 0x3e38aa3b, v90
	v_cndmask_b32_e32 v90, v228, v192, vcc
	v_cmp_lt_i32_e32 vcc, 0xfffffff1, v114
	s_and_b64 vcc, s[0:1], vcc
	v_fmac_f32_e32 v193, 0x3e38aa3b, v91
	v_cndmask_b32_e32 v91, v228, v193, vcc
	v_cmp_lt_i32_e32 vcc, 0xfffffff2, v114
	s_and_b64 vcc, s[0:1], vcc
	v_fmac_f32_e32 v194, 0x3e38aa3b, v92
	v_cndmask_b32_e32 v92, v228, v194, vcc
	v_cmp_lt_i32_e32 vcc, 0xfffffff3, v114
	s_and_b64 vcc, s[0:1], vcc
	v_fmac_f32_e32 v195, 0x3e38aa3b, v93
	v_cndmask_b32_e32 v93, v228, v195, vcc
	v_mov_b32_e32 v114, 1.0
	v_mov_b32_e32 v120, 0
	s_branch .Lsel_BdY_common

; __device__ __forceinline__ bf16x8 pack_p(const float* a, const float* b) { u32x4 w; w.x = cvtpk(a[0], a[1]); w.y = cvtpk(a[2], a[3]); w.z = cvtpk(b[0], b[1]); w.w = cvtpk(b[2], b[3]); return __builtin_bit_cast(bf16x8, w); }
; #define AT_LOAD(s_, k_, v_) do { k_ = *(const u32x4*)(kg + (size_t)(s_) * 4096); v_ = *(const u32x4*)(vg + (s_) * 64); } while (0)
; template <int MODE>
; __device__ __forceinline__ void attn_step(const unsigned char* sb, int st, const bf16x8 qf0, const bf16x8 qf1, int t, int p0, bool sel, const float* bias, float cfar, f32x4 (&o)[4], float& mrun, float& lrun,
;                                           int koff, int voff, int q4) {
;     ...
;     f32x4 ps4 = {0.f, 0.f, 0.f, 0.f};
;     const float foff = fc - mnew;
; #pragma unroll
;     for (int kt = 0; kt < 4; ++kt) {
;         s[kt] = s[kt] * fsc + foff;
; #pragma unroll
;         for (int j = 0; j < 4; ++j) s[kt][j] = __builtin_amdgcn_exp2f(s[kt][j]);
;         ps4 += s[kt];
;     }
;     const float ps = (ps4.x + ps4.y) + (ps4.z + ps4.w);
;     if (__ballot(mnew != mrun) != 0ull) {
;         const float alpha = __builtin_amdgcn_exp2f(mrun - mnew);
;         lrun *= alpha;
; #pragma unroll
;         for (int dt = 0; dt < 4; ++dt) o[dt] *= alpha;
;     }
;     lrun += ps; mrun = mnew;
;     float pa[4][4];
; #pragma unroll
;     for (int kt = 0; kt < 4; ++kt)
; #pragma unroll
;         for (int j = 0; j < 4; ++j) pa[kt][j] = s[kt][j];
;     const bf16x8 pf0 = pack_p(pa[0], pa[1]), pf1 = pack_p(pa[2], pa[3]);
; #pragma unroll
;     for (int dt = 0; dt < 4; ++dt) {
;         o[dt] = __builtin_amdgcn_mfma_f32_16x16x32_bf16(vfr[dt][0], pf0, o[dt], 0, 0, 0); o[dt] = __builtin_amdgcn_mfma_f32_16x16x32_bf16(vfr[dt][1], pf1, o[dt], 0, 0, 0);
;     }
; template <int MODE> ...
;     ...
;     const int crow = tid >> 3, cch = tid & 7;
;     const bf16* kg = K + (size_t)crow * 64 + cch * 8;
;     const bf16* vg = VT + (size_t)crow * 2048 + cch * 8;
;     const int kdst = crow * AKP + cch * 16;
;     const int vdst = 9216 + crow * AKP + ((cch >> 2) * 32 + (cch & 1) * 16 + ((cch & 3) >> 1) * 4) * 2;
;     const int koff = qi * AKP + q4 * 16, voff = 9216 + qi * AKP + q4 * 16;
;     unsigned char* sb0 = lds + AL_KV0; unsigned char* sb1 = sb0 + KV_STAGE;
;     ...
;     u32x4 ka, va, kb = {0u, 0u, 0u, 0u}, vb = {0u, 0u, 0u, 0u};
;     AT_LOAD(st_lo, ka, va);
;     if (st_lo + 1 <= st_hi) AT_LOAD(st_lo + 1, kb, vb);
.Lsel_BdY_616:
	v_sub_f32_e32 v120, v120, v118
	v_pk_fma_f32 v[104:105], v[104:105], v[114:115], v[120:121] op_sel_hi:[1,0,0]
	v_pk_fma_f32 v[102:103], v[102:103], v[114:115], v[120:121] op_sel_hi:[1,0,0]
	v_exp_f32_e32 v104, v104
	v_exp_f32_e32 v102, v102
	v_exp_f32_e32 v103, v103
	v_exp_f32_e32 v105, v105
	v_pk_fma_f32 v[100:101], v[100:101], v[114:115], v[120:121] op_sel_hi:[1,0,0]
	v_pk_fma_f32 v[98:99], v[98:99], v[114:115], v[120:121] op_sel_hi:[1,0,0]
	v_exp_f32_e32 v100, v100
	v_exp_f32_e32 v98, v98
	v_exp_f32_e32 v99, v99
	v_exp_f32_e32 v101, v101
	v_pk_fma_f32 v[96:97], v[96:97], v[114:115], v[120:121] op_sel_hi:[1,0,0]
	v_pk_fma_f32 v[94:95], v[94:95], v[114:115], v[120:121] op_sel_hi:[1,0,0]
	v_exp_f32_e32 v96, v96
	v_exp_f32_e32 v94, v94
	v_exp_f32_e32 v95, v95
	v_exp_f32_e32 v97, v97
	v_pk_fma_f32 v[92:93], v[92:93], v[114:115], v[120:121] op_sel_hi:[1,0,0]
	v_pk_fma_f32 v[90:91], v[90:91], v[114:115], v[120:121] op_sel_hi:[1,0,0]
	v_exp_f32_e32 v146, v92
	v_exp_f32_e32 v120, v90
	v_exp_f32_e32 v121, v91
	v_exp_f32_e32 v147, v93
	v_pk_add_f32 v[132:133], v[102:103], 0 op_sel_hi:[1,0]
	v_pk_add_f32 v[134:135], v[104:105], 0 op_sel_hi:[1,0]
	v_pk_add_f32 v[132:133], v[98:99], v[132:133]
	v_pk_add_f32 v[134:135], v[100:101], v[134:135]
	v_pk_add_f32 v[132:133], v[94:95], v[132:133]
	v_pk_add_f32 v[134:135], v[96:97], v[134:135]
	v_pk_add_f32 v[92:93], v[120:121], v[132:133]
	v_pk_add_f32 v[90:91], v[146:147], v[134:135]
	v_cvt_pk_bf16_f32 v94, v94, v95
	v_pk_mov_b32 v[132:133], v[92:93], v[90:91] op_sel:[1,0]
	v_mov_b32_e32 v93, v91
	v_pk_add_f32 v[90:91], v[132:133], v[92:93]
	v_cvt_pk_bf16_f32 v92, v98, v99
	v_add_f32_e32 v90, v90, v91
	v_add_f32_e32 v117, v90, v117
	v_cvt_pk_bf16_f32 v90, v102, v103
	v_cvt_pk_bf16_f32 v91, v104, v105
	v_cvt_pk_bf16_f32 v93, v100, v101
	v_cvt_pk_bf16_f32 v95, v96, v97
	v_cvt_pk_bf16_f32 v96, v120, v121
	s_waitcnt lgkmcnt(0)
	v_mfma_f32_16x16x32_bf16 v[46:49], v[86:89], v[90:93], v[46:49]
	v_cvt_pk_bf16_f32 v97, v146, v147
	v_mfma_f32_16x16x32_bf16 v[42:45], v[78:81], v[90:93], v[42:45]
	v_mfma_f32_16x16x32_bf16 v[50:53], v[70:73], v[90:93], v[50:53]
	v_mfma_f32_16x16x32_bf16 v[54:57], v[62:65], v[90:93], v[54:57]
	v_mfma_f32_16x16x32_bf16 v[46:49], v[82:85], v[94:97], v[46:49]
	v_mfma_f32_16x16x32_bf16 v[42:45], v[74:77], v[94:97], v[42:45]
	v_mfma_f32_16x16x32_bf16 v[50:53], v[66:69], v[94:97], v[50:53]
	v_mfma_f32_16x16x32_bf16 v[54:57], v[58:61], v[94:97], v[54:57]
	s_mov_b32 s10, 0
	v_writelane_b32 v255, s10, 60
	s_nop 1
	v_readlane_b32 s10, v255, 61
	s_nop 3
	s_cmp_eq_u32 s10, 1
	s_cbranch_scc1 .Lsel_exit_go
	s_branch .Lsel_X_go
.LBB0_618:
	s_cmp_eq_u32 s32, 0
	s_cbranch_scc1 .Lsel_exit_go
	v_readlane_b32 s10, v255, 60
	s_nop 3
	s_cmp_eq_u32 s10, 0
	s_cbranch_scc1 .Lsel_exit_go
	s_mov_b32 s0, 1
	v_writelane_b32 v255, s0, 61
	s_cmp_eq_u32 s10, 1
	s_cbranch_scc1 .Lsel_BdX
	s_branch .Lsel_BdY
.Lsel_exit_go:
	s_mov_b32 s0, 0
	v_writelane_b32 v255, s0, 61
	s_lshl_b32 s6, s12, 1
	v_readlane_b32 s0, v255, 47
	s_add_u32 s0, s0, s6
	v_readlane_b32 s1, v255, 48
	s_addc_u32 s1, s1, 0
	v_readlane_b32 s7, v255, 49
	s_add_u32 s10, s7, s6
	v_readlane_b32 s6, v255, 50
	s_addc_u32 s11, s6, 0
	s_addk_i32 s96, 0xfe01
	s_lshr_b32 s12, s96, 6
	s_and_b64 s[6:7], s[86:87], exec
	s_cselect_b32 s6, s12, 0
	s_waitcnt vmcnt(1)
	v_lshl_add_u64 v[2:3], s[0:1], 0, v[106:107]
	v_lshlrev_b32_e32 v4, 1, v116
	v_mov_b32_e32 v5, v1
	s_mov_b32 s7, s39
	v_lshl_add_u64 v[2:3], v[2:3], 0, v[4:5]
	s_waitcnt vmcnt(0)
	v_lshl_add_u64 v[6:7], s[10:11], 0, v[108:109]
	s_lshl_b64 s[12:13], s[6:7], 13
	v_lshl_add_u64 v[132:133], v[6:7], 0, v[4:5]
	v_lshl_add_u64 v[4:5], v[2:3], 0, s[12:13]
	s_lshl_b32 s10, s6, 6
	s_mov_b32 s11, s39
	v_lshl_add_u64 v[6:7], s[10:11], 1, v[132:133]
	global_load_dwordx4 v[58:61], v[4:5], off
	global_load_dwordx4 v[62:65], v[6:7], off
	ds_bpermute_b32 v4, v136, v117
	s_cmp_ge_u32 s6, s97
	s_waitcnt lgkmcnt(0)
	v_add_f32_e32 v127, v117, v4
	ds_bpermute_b32 v131, v137, v127
	s_cbranch_scc1 .LBB0_620
	s_add_i32 s0, s6, 1
	s_mov_b32 s1, s39
	s_lshl_b32 s14, s0, 7
	s_lshl_b64 s[0:1], s[0:1], 13
	s_mov_b32 s15, s39
	v_lshl_add_u64 v[2:3], v[2:3], 0, s[0:1]
	v_lshl_add_u64 v[4:5], v[132:133], 0, s[14:15]
	global_load_dwordx4 v[70:73], v[2:3], off
	global_load_dwordx4 v[66:69], v[4:5], off
	s_branch .LBB0_621
